# helper: hoist r-slot LDS address (v185 computed once per 8 stages, stage 2 uses private v196), drop 7 redundant vmcnt(38) waits that were directly followed by vmcnt(36)
# baseline (speedup 1.0000x reference)
.LBB0_182:
	s_min_u32 s4, s37, 0x1030
	s_lshl_b32 s4, s4, 2
	s_cmp_gt_u32 s37, 48
	s_cselect_b32 s5, 0xffffff3c, 60
	s_cselect_b32 s23, s10, s33
	s_cselect_b32 s37, s46, 0xfc
	s_add_i32 s44, s4, s5
	s_sub_i32 s37, s37, s44
	s_waitcnt vmcnt(38)
	s_and_b64 s[4:5], s[42:43], exec
	s_waitcnt vmcnt(36)
	v_fma_mix_f32 v188, v91, v2, v92 op_sel:[0,0,0] op_sel_hi:[1,0,0]
	v_fma_mix_f32 v189, v91, v3, v93 op_sel:[1,0,0] op_sel_hi:[1,0,0]
	v_fma_mix_f32 v190, v90, v0, v94 op_sel:[0,0,0] op_sel_hi:[1,0,0]
	v_fma_mix_f32 v191, v90, v1, v95 op_sel:[1,0,0] op_sel_hi:[1,0,0]
	v_fma_mix_f32 v192, v103, v188, 0 op_sel:[0,0,0] op_sel_hi:[1,0,0]
	v_fma_mix_f32 v193, v103, v189, 0 op_sel:[1,0,0] op_sel_hi:[1,0,0]
	v_fma_mix_f32 v194, v102, v190, 0 op_sel:[0,0,0] op_sel_hi:[1,0,0]
	v_fma_mix_f32 v195, v102, v191, 0 op_sel:[1,0,0] op_sel_hi:[1,0,0]
	s_cselect_b32 s4, s44, s37
	s_add_i32 s4, s4, s23
	s_ashr_i32 s5, s4, 31
	s_lshl_b64 s[4:5], s[4:5], 11
	v_add_u32_e32 v187, s4, v119
	v_pk_mul_f16 v123, v91, v35
	v_pk_mul_f16 v122, v90, v34
	v_cvt_pk_f16_f32 v125, v192, v193
	v_cvt_pk_f16_f32 v124, v194, v195
	ds_write_b128 v120, v[32:35] offset:21504
	ds_write_b128 v120, v[122:125] offset:22528
	s_waitcnt vmcnt(35)
	ds_write_b64 v185, v[100:101] offset:23552
	v_mov_b32_e32 v32, s22
	s_waitcnt lgkmcnt(0)
	ds_write_b32 v161, v32 offset:49152
	global_load_dwordx2 v[32:33], v187, s[74:75]
	global_load_dwordx2 v[90:91], v187, s[76:77]
	global_load_dwordx2 v[34:35], v187, s[78:79]
	global_load_dwordx2 v[102:103], v187, s[80:81]
	global_load_dwordx2 v[100:101], v187, s[82:83]
	s_nop 0
	s_andn2_b64 vcc, exec, s[90:91]
	s_mov_b32 s37, s22
	s_cbranch_vccz .LBB0_242

.LBB0_185:
	s_waitcnt vmcnt(36)
	s_and_b32 s4, s37, 8
	s_mulk_i32 s4, 0xc00
	s_add_i32 s4, s4, 16
	s_or_b32 s23, s37, 1
	s_add_i32 s22, s37, 8
	s_cmpk_gt_u32 s37, 0x1037
	v_fma_mix_f32 v188, v36, v0, v94 op_sel:[0,0,0] op_sel_hi:[1,0,0]
	v_fma_mix_f32 v189, v36, v1, v95 op_sel:[1,0,0] op_sel_hi:[1,0,0]
	v_fma_mix_f32 v190, v37, v2, v92 op_sel:[0,0,0] op_sel_hi:[1,0,0]
	v_fma_mix_f32 v191, v37, v3, v93 op_sel:[1,0,0] op_sel_hi:[1,0,0]
	v_fma_mix_f32 v192, v44, v188, 0 op_sel:[0,0,0] op_sel_hi:[1,0,0]
	v_fma_mix_f32 v193, v44, v189, 0 op_sel:[1,0,0] op_sel_hi:[1,0,0]
	v_fma_mix_f32 v194, v45, v190, 0 op_sel:[0,0,0] op_sel_hi:[1,0,0]
	v_fma_mix_f32 v195, v45, v191, 0 op_sel:[1,0,0] op_sel_hi:[1,0,0]
	v_pk_mul_f16 v122, v36, v6
	v_cvt_pk_f16_f32 v124, v192, v193
	v_add_u32_e32 v36, s4, v113
	v_add_u32_e32 v121, s4, v111
	s_cselect_b64 s[90:91], -1, 0
	s_lshl_b32 s4, s22, 2
	s_cmpk_lt_u32 s37, 0x1038
	s_cselect_b32 s4, s4, 0x40fc
	s_add_i32 s5, s4, 0xffffff00
	s_min_u32 s44, s5, s4
	s_cmpk_gt_u32 s4, 0xff
	s_movk_i32 s4, 0x3fff
	s_cselect_b32 s4, s4, 0xff
	s_cselect_b32 s45, s10, s33
	s_sub_i32 s4, s4, s44
	s_add_i32 vcc_lo, s4, -3
	s_and_b64 s[4:5], s[42:43], exec
	s_cselect_b32 s4, s44, vcc_lo
	s_add_i32 s4, s4, s45
	s_ashr_i32 s5, s4, 31
	s_lshl_b64 s[4:5], s[4:5], 11
	v_add_u32_e32 v187, s4, v119
	v_add_u32_e32 v120, v36, v128
	v_pk_mul_f16 v123, v37, v7
	v_cvt_pk_f16_f32 v125, v194, v195
	ds_write_b128 v120, v[4:7]
	ds_write_b128 v120, v[122:125] offset:1024
	s_waitcnt vmcnt(35)
	v_add_u32_e32 v185, v121, v186
	ds_write_b64 v185, v[38:39] offset:2048
	v_mov_b32_e32 v4, s23
	s_waitcnt lgkmcnt(0)
	ds_write_b32 v161, v4 offset:49152
	global_load_dwordx2 v[4:5], v187, s[74:75]
	global_load_dwordx2 v[36:37], v187, s[76:77]
	global_load_dwordx2 v[6:7], v187, s[78:79]
	global_load_dwordx2 v[44:45], v187, s[80:81]
	global_load_dwordx2 v[38:39], v187, s[82:83]
	s_nop 0
	v_cndmask_b32_e64 v122, 0, 1, s[92:93]
	v_cmp_ne_u32_e64 s[44:45], 1, v122
	s_andn2_b64 vcc, exec, s[92:93]
	s_cbranch_vccnz .LBB0_187
	s_add_i32 s4, s37, -14
	s_cmp_ge_i32 s36, s4
	s_cbranch_scc0 .LBB0_203
.LBB0_187:
	s_waitcnt vmcnt(36)
	v_fma_mix_f32 v188, v41, v2, v92 op_sel:[0,0,0] op_sel_hi:[1,0,0]
	v_fma_mix_f32 v189, v41, v3, v93 op_sel:[1,0,0] op_sel_hi:[1,0,0]
	v_fma_mix_f32 v190, v40, v0, v94 op_sel:[0,0,0] op_sel_hi:[1,0,0]
	v_fma_mix_f32 v191, v40, v1, v95 op_sel:[1,0,0] op_sel_hi:[1,0,0]
	v_fma_mix_f32 v192, v53, v188, 0 op_sel:[0,0,0] op_sel_hi:[1,0,0]
	v_fma_mix_f32 v193, v53, v189, 0 op_sel:[1,0,0] op_sel_hi:[1,0,0]
	v_fma_mix_f32 v194, v52, v190, 0 op_sel:[0,0,0] op_sel_hi:[1,0,0]
	v_fma_mix_f32 v195, v52, v191, 0 op_sel:[1,0,0] op_sel_hi:[1,0,0]
	s_and_b32 s4, s23, 9
	s_mulk_i32 s4, 0xc00
	s_add_i32 s4, s4, 16
	v_pk_mul_f16 v122, v40, v10
	v_add3_u32 v40, s4, v113, v128
	v_pk_mul_f16 v123, v41, v11
	v_cvt_pk_f16_f32 v125, v192, v193
	v_cvt_pk_f16_f32 v124, v194, v195
	ds_write_b128 v40, v[8:11]
	ds_write_b128 v40, v[122:125] offset:1024
	v_add_u32_e32 v8, s4, v111
	s_or_b32 s4, s37, 2
	s_waitcnt vmcnt(35)
	v_add_u32_e32 v196, v8, v186
	ds_write_b64 v196, v[46:47] offset:2048
	v_mov_b32_e32 v8, s4
	s_min_u32 s4, s37, 0x1036
	s_lshl_b32 s4, s4, 2
	s_cmp_gt_u32 s37, 54
	s_cselect_b32 s5, 0xffffff24, 36
	s_cselect_b32 s23, s10, s33
	s_cselect_b32 s92, s46, 0xfc
	s_add_i32 s93, s4, s5
	s_sub_i32 s92, s92, s93
	s_and_b64 s[4:5], s[42:43], exec
	s_cselect_b32 s4, s93, s92
	s_add_i32 s4, s4, s23
	s_ashr_i32 s5, s4, 31
	s_lshl_b64 s[4:5], s[4:5], 11
	v_add_u32_e32 v187, s4, v119
	s_waitcnt lgkmcnt(0)
	ds_write_b32 v161, v8 offset:49152
	global_load_dwordx2 v[8:9], v187, s[74:75]
	global_load_dwordx2 v[40:41], v187, s[76:77]
	global_load_dwordx2 v[10:11], v187, s[78:79]
	global_load_dwordx2 v[52:53], v187, s[80:81]
	global_load_dwordx2 v[46:47], v187, s[82:83]
	s_nop 0
	s_and_b64 vcc, exec, s[44:45]
	s_cbranch_vccnz .LBB0_189
	s_add_i32 s4, s37, -13
	s_cmp_ge_i32 s36, s4
	s_cbranch_scc0 .LBB0_206
.LBB0_189:
	s_waitcnt vmcnt(36)
	v_fma_mix_f32 v188, v49, v2, v92 op_sel:[0,0,0] op_sel_hi:[1,0,0]
	v_fma_mix_f32 v189, v49, v3, v93 op_sel:[1,0,0] op_sel_hi:[1,0,0]
	v_fma_mix_f32 v190, v48, v0, v94 op_sel:[0,0,0] op_sel_hi:[1,0,0]
	v_fma_mix_f32 v191, v48, v1, v95 op_sel:[1,0,0] op_sel_hi:[1,0,0]
	v_fma_mix_f32 v192, v61, v188, 0 op_sel:[0,0,0] op_sel_hi:[1,0,0]
	v_fma_mix_f32 v193, v61, v189, 0 op_sel:[1,0,0] op_sel_hi:[1,0,0]
	v_fma_mix_f32 v194, v60, v190, 0 op_sel:[0,0,0] op_sel_hi:[1,0,0]
	v_fma_mix_f32 v195, v60, v191, 0 op_sel:[1,0,0] op_sel_hi:[1,0,0]
	s_or_b32 s4, s37, 3
	v_pk_mul_f16 v123, v49, v15
	v_pk_mul_f16 v122, v48, v14
	v_cvt_pk_f16_f32 v125, v192, v193
	v_cvt_pk_f16_f32 v124, v194, v195
	ds_write_b128 v120, v[12:15] offset:6144
	ds_write_b128 v120, v[122:125] offset:7168
	s_waitcnt vmcnt(35)
	ds_write_b64 v185, v[54:55] offset:8192
	v_mov_b32_e32 v12, s4
	s_min_u32 s4, s37, 0x1035
	s_lshl_b32 s4, s4, 2
	s_cmp_gt_u32 s37, 53
	s_cselect_b32 s5, 0xffffff28, 40
	s_cselect_b32 s23, s10, s33
	s_cselect_b32 s92, s46, 0xfc
	s_add_i32 s93, s4, s5
	s_sub_i32 s92, s92, s93
	s_and_b64 s[4:5], s[42:43], exec
	s_cselect_b32 s4, s93, s92
	s_add_i32 s4, s4, s23
	s_ashr_i32 s5, s4, 31
	s_lshl_b64 s[4:5], s[4:5], 11
	v_add_u32_e32 v187, s4, v119
	s_waitcnt lgkmcnt(0)
	ds_write_b32 v161, v12 offset:49152
	global_load_dwordx2 v[12:13], v187, s[74:75]
	global_load_dwordx2 v[48:49], v187, s[76:77]
	global_load_dwordx2 v[14:15], v187, s[78:79]
	global_load_dwordx2 v[60:61], v187, s[80:81]
	global_load_dwordx2 v[54:55], v187, s[82:83]
	s_nop 0
	s_and_b64 vcc, exec, s[44:45]
	s_cbranch_vccnz .LBB0_191
	s_add_i32 s4, s37, -12
	s_cmp_ge_i32 s36, s4
	s_cbranch_scc0 .LBB0_209
.LBB0_191:
	s_waitcnt vmcnt(36)
	v_fma_mix_f32 v188, v57, v2, v92 op_sel:[0,0,0] op_sel_hi:[1,0,0]
	v_fma_mix_f32 v189, v57, v3, v93 op_sel:[1,0,0] op_sel_hi:[1,0,0]
	v_fma_mix_f32 v190, v56, v0, v94 op_sel:[0,0,0] op_sel_hi:[1,0,0]
	v_fma_mix_f32 v191, v56, v1, v95 op_sel:[1,0,0] op_sel_hi:[1,0,0]
	v_fma_mix_f32 v192, v67, v188, 0 op_sel:[0,0,0] op_sel_hi:[1,0,0]
	v_fma_mix_f32 v193, v67, v189, 0 op_sel:[1,0,0] op_sel_hi:[1,0,0]
	v_fma_mix_f32 v194, v66, v190, 0 op_sel:[0,0,0] op_sel_hi:[1,0,0]
	v_fma_mix_f32 v195, v66, v191, 0 op_sel:[1,0,0] op_sel_hi:[1,0,0]
	s_or_b32 s4, s37, 4
	v_pk_mul_f16 v123, v57, v19
	v_pk_mul_f16 v122, v56, v18
	v_cvt_pk_f16_f32 v125, v192, v193
	v_cvt_pk_f16_f32 v124, v194, v195
	ds_write_b128 v120, v[16:19] offset:9216
	ds_write_b128 v120, v[122:125] offset:10240
	s_waitcnt vmcnt(35)
	ds_write_b64 v185, v[62:63] offset:11264
	v_mov_b32_e32 v16, s4
	s_min_u32 s4, s37, 0x1034
	s_lshl_b32 s4, s4, 2
	s_cmp_gt_u32 s37, 52
	s_cselect_b32 s5, 0xffffff2c, 44
	s_cselect_b32 s23, s10, s33
	s_cselect_b32 s92, s46, 0xfc
	s_add_i32 s93, s4, s5
	s_sub_i32 s92, s92, s93
	s_and_b64 s[4:5], s[42:43], exec
	s_cselect_b32 s4, s93, s92
	s_add_i32 s4, s4, s23
	s_ashr_i32 s5, s4, 31
	s_lshl_b64 s[4:5], s[4:5], 11
	v_add_u32_e32 v187, s4, v119
	s_waitcnt lgkmcnt(0)
	ds_write_b32 v161, v16 offset:49152
	global_load_dwordx2 v[16:17], v187, s[74:75]
	global_load_dwordx2 v[56:57], v187, s[76:77]
	global_load_dwordx2 v[18:19], v187, s[78:79]
	global_load_dwordx2 v[66:67], v187, s[80:81]
	global_load_dwordx2 v[62:63], v187, s[82:83]
	s_nop 0
	s_and_b64 vcc, exec, s[44:45]
	s_cbranch_vccnz .LBB0_193
	s_add_i32 s4, s37, -11
	s_cmp_ge_i32 s36, s4
	s_cbranch_scc0 .LBB0_212
.LBB0_193:
	s_waitcnt vmcnt(36)
	v_fma_mix_f32 v188, v65, v2, v92 op_sel:[0,0,0] op_sel_hi:[1,0,0]
	v_fma_mix_f32 v189, v65, v3, v93 op_sel:[1,0,0] op_sel_hi:[1,0,0]
	v_fma_mix_f32 v190, v64, v0, v94 op_sel:[0,0,0] op_sel_hi:[1,0,0]
	v_fma_mix_f32 v191, v64, v1, v95 op_sel:[1,0,0] op_sel_hi:[1,0,0]
	v_fma_mix_f32 v192, v77, v188, 0 op_sel:[0,0,0] op_sel_hi:[1,0,0]
	v_fma_mix_f32 v193, v77, v189, 0 op_sel:[1,0,0] op_sel_hi:[1,0,0]
	v_fma_mix_f32 v194, v76, v190, 0 op_sel:[0,0,0] op_sel_hi:[1,0,0]
	v_fma_mix_f32 v195, v76, v191, 0 op_sel:[1,0,0] op_sel_hi:[1,0,0]
	s_or_b32 s4, s37, 5
	v_pk_mul_f16 v123, v65, v23
	v_pk_mul_f16 v122, v64, v22
	v_cvt_pk_f16_f32 v125, v192, v193
	v_cvt_pk_f16_f32 v124, v194, v195
	ds_write_b128 v120, v[20:23] offset:12288
	ds_write_b128 v120, v[122:125] offset:13312
	s_waitcnt vmcnt(35)
	ds_write_b64 v185, v[70:71] offset:14336
	v_mov_b32_e32 v20, s4
	s_min_u32 s4, s37, 0x1033
	s_lshl_b32 s4, s4, 2
	s_cmp_gt_u32 s37, 51
	s_cselect_b32 s5, 0xffffff30, 48
	s_cselect_b32 s23, s10, s33
	s_cselect_b32 s92, s46, 0xfc
	s_add_i32 s93, s4, s5
	s_sub_i32 s92, s92, s93
	s_and_b64 s[4:5], s[42:43], exec
	s_cselect_b32 s4, s93, s92
	s_add_i32 s4, s4, s23
	s_ashr_i32 s5, s4, 31
	s_lshl_b64 s[4:5], s[4:5], 11
	v_add_u32_e32 v187, s4, v119
	s_waitcnt lgkmcnt(0)
	ds_write_b32 v161, v20 offset:49152
	global_load_dwordx2 v[20:21], v187, s[74:75]
	global_load_dwordx2 v[64:65], v187, s[76:77]
	global_load_dwordx2 v[22:23], v187, s[78:79]
	global_load_dwordx2 v[76:77], v187, s[80:81]
	global_load_dwordx2 v[70:71], v187, s[82:83]
	s_nop 0
	s_and_b64 vcc, exec, s[44:45]
	s_cbranch_vccnz .LBB0_195
	s_add_i32 s4, s37, -10
	s_cmp_ge_i32 s36, s4
	s_cbranch_scc0 .LBB0_215
.LBB0_195:
	s_waitcnt vmcnt(36)
	v_fma_mix_f32 v188, v73, v2, v92 op_sel:[0,0,0] op_sel_hi:[1,0,0]
	v_fma_mix_f32 v189, v73, v3, v93 op_sel:[1,0,0] op_sel_hi:[1,0,0]
	v_fma_mix_f32 v190, v72, v0, v94 op_sel:[0,0,0] op_sel_hi:[1,0,0]
	v_fma_mix_f32 v191, v72, v1, v95 op_sel:[1,0,0] op_sel_hi:[1,0,0]
	v_fma_mix_f32 v192, v85, v188, 0 op_sel:[0,0,0] op_sel_hi:[1,0,0]
	v_fma_mix_f32 v193, v85, v189, 0 op_sel:[1,0,0] op_sel_hi:[1,0,0]
	v_fma_mix_f32 v194, v84, v190, 0 op_sel:[0,0,0] op_sel_hi:[1,0,0]
	v_fma_mix_f32 v195, v84, v191, 0 op_sel:[1,0,0] op_sel_hi:[1,0,0]
	s_or_b32 s4, s37, 6
	v_pk_mul_f16 v123, v73, v27
	v_pk_mul_f16 v122, v72, v26
	v_cvt_pk_f16_f32 v125, v192, v193
	v_cvt_pk_f16_f32 v124, v194, v195
	ds_write_b128 v120, v[24:27] offset:15360
	ds_write_b128 v120, v[122:125] offset:16384
	s_waitcnt vmcnt(35)
	ds_write_b64 v185, v[78:79] offset:17408
	v_mov_b32_e32 v24, s4
	s_min_u32 s4, s37, 0x1032
	s_lshl_b32 s4, s4, 2
	s_cmp_gt_u32 s37, 50
	s_cselect_b32 s5, 0xffffff34, 52
	s_cselect_b32 s23, s10, s33
	s_cselect_b32 s92, s46, 0xfc
	s_add_i32 s93, s4, s5
	s_sub_i32 s92, s92, s93
	s_and_b64 s[4:5], s[42:43], exec
	s_cselect_b32 s4, s93, s92
	s_add_i32 s4, s4, s23
	s_ashr_i32 s5, s4, 31
	s_lshl_b64 s[4:5], s[4:5], 11
	v_add_u32_e32 v187, s4, v119
	s_waitcnt lgkmcnt(0)
	ds_write_b32 v161, v24 offset:49152
	global_load_dwordx2 v[24:25], v187, s[74:75]
	global_load_dwordx2 v[72:73], v187, s[76:77]
	global_load_dwordx2 v[26:27], v187, s[78:79]
	global_load_dwordx2 v[84:85], v187, s[80:81]
	global_load_dwordx2 v[78:79], v187, s[82:83]
	s_nop 0
	s_and_b64 vcc, exec, s[44:45]
	s_cbranch_vccnz .LBB0_197
	s_add_i32 s4, s37, -9
	s_cmp_ge_i32 s36, s4
	s_cbranch_scc0 .LBB0_218
.LBB0_197:
	s_waitcnt vmcnt(36)
	v_fma_mix_f32 v188, v83, v2, v92 op_sel:[0,0,0] op_sel_hi:[1,0,0]
	v_fma_mix_f32 v189, v83, v3, v93 op_sel:[1,0,0] op_sel_hi:[1,0,0]
	v_fma_mix_f32 v190, v82, v0, v94 op_sel:[0,0,0] op_sel_hi:[1,0,0]
	v_fma_mix_f32 v191, v82, v1, v95 op_sel:[1,0,0] op_sel_hi:[1,0,0]
	v_fma_mix_f32 v192, v99, v188, 0 op_sel:[0,0,0] op_sel_hi:[1,0,0]
	v_fma_mix_f32 v193, v99, v189, 0 op_sel:[1,0,0] op_sel_hi:[1,0,0]
	v_fma_mix_f32 v194, v98, v190, 0 op_sel:[0,0,0] op_sel_hi:[1,0,0]
	v_fma_mix_f32 v195, v98, v191, 0 op_sel:[1,0,0] op_sel_hi:[1,0,0]
	s_or_b32 s4, s37, 7
	v_pk_mul_f16 v123, v83, v31
	v_pk_mul_f16 v122, v82, v30
	v_cvt_pk_f16_f32 v125, v192, v193
	v_cvt_pk_f16_f32 v124, v194, v195
	ds_write_b128 v120, v[28:31] offset:18432
	ds_write_b128 v120, v[122:125] offset:19456
	s_waitcnt vmcnt(35)
	ds_write_b64 v185, v[88:89] offset:20480
	v_mov_b32_e32 v28, s4
	s_min_u32 s4, s37, 0x1031
	s_lshl_b32 s4, s4, 2
	s_cmp_gt_u32 s37, 49
	s_cselect_b32 s5, 0xffffff38, 56
	s_cselect_b32 s23, s10, s33
	s_cselect_b32 s92, s46, 0xfc
	s_add_i32 s93, s4, s5
	s_sub_i32 s92, s92, s93
	s_and_b64 s[4:5], s[42:43], exec
	s_cselect_b32 s4, s93, s92
	s_add_i32 s4, s4, s23
	s_ashr_i32 s5, s4, 31
	s_lshl_b64 s[4:5], s[4:5], 11
	v_add_u32_e32 v187, s4, v119
	s_waitcnt lgkmcnt(0)
	ds_write_b32 v161, v28 offset:49152
	global_load_dwordx2 v[28:29], v187, s[74:75]
	global_load_dwordx2 v[82:83], v187, s[76:77]
	global_load_dwordx2 v[30:31], v187, s[78:79]
	global_load_dwordx2 v[98:99], v187, s[80:81]
	global_load_dwordx2 v[88:89], v187, s[82:83]
	s_nop 0
	s_and_b64 vcc, exec, s[44:45]
	s_cbranch_vccnz .LBB0_182
	s_add_i32 s4, s37, -8
	s_cmp_ge_i32 s36, s4
	s_cbranch_scc0 .LBB0_221
	s_branch .LBB0_182
